# v55 + P6 unit pairing tweak: for the 32 heaviest first units the partner keeps the same half (balances near-diagonal tiles across workgroups)
# baseline (speedup 1.0000x reference)
.LBB0_714:
	s_sub_i32 s77, 0x1ff, s79
	s_cmp_lt_u32 s79, 32
	s_cselect_b32 s0, 1, 0
	s_xor_b32 s77, s77, s0
	s_mov_b64 s[86:87], -1
	s_branch .LBB0_717
